# SSD scan: state-decay factors exp2(cum_last-cum_j) computed once per chunk by 128 lanes into an LDS table (was recomputed by every wave); decode-attention PV loop loads batched
# speedup vs baseline: 1.0214x; 1.0048x over previous
.LBB0_1478:
	s_mov_b32 s26, 0x0
	s_mov_b32 s27, 0
	v_lshl_add_u64 v[198:199], v[6:7], 0, s[26:27]
	s_mov_b32 s26, 0x10000
	v_lshl_add_u64 v[200:201], v[6:7], 0, s[26:27]
	global_load_dword v118, v[198:199], off
	global_load_dword v119, v[200:201], off
	s_mov_b32 s26, 0x0
	s_mov_b32 s27, 0
	v_lshl_add_u64 v[198:199], v[6:7], 0, s[26:27]
	s_mov_b32 s26, 0x10000
	v_lshl_add_u64 v[200:201], v[6:7], 0, s[26:27]
	global_load_dword v120, v[198:199], off offset:1024
	global_load_dword v121, v[200:201], off offset:1024
	s_mov_b32 s26, 0x0
	s_mov_b32 s27, 0
	v_lshl_add_u64 v[198:199], v[6:7], 0, s[26:27]
	s_mov_b32 s26, 0x10000
	v_lshl_add_u64 v[200:201], v[6:7], 0, s[26:27]
	global_load_dword v122, v[198:199], off offset:2048
	global_load_dword v123, v[200:201], off offset:2048
	s_mov_b32 s26, 0x0
	s_mov_b32 s27, 0
	v_lshl_add_u64 v[198:199], v[6:7], 0, s[26:27]
	s_mov_b32 s26, 0x10000
	v_lshl_add_u64 v[200:201], v[6:7], 0, s[26:27]
	global_load_dword v124, v[198:199], off offset:3072
	global_load_dword v125, v[200:201], off offset:3072
	s_mov_b32 s26, 0x1000
	s_mov_b32 s27, 0
	v_lshl_add_u64 v[198:199], v[6:7], 0, s[26:27]
	s_mov_b32 s26, 0x11000
	v_lshl_add_u64 v[200:201], v[6:7], 0, s[26:27]
	global_load_dword v126, v[198:199], off
	global_load_dword v127, v[200:201], off
	s_mov_b32 s26, 0x1000
	s_mov_b32 s27, 0
	v_lshl_add_u64 v[198:199], v[6:7], 0, s[26:27]
	s_mov_b32 s26, 0x11000
	v_lshl_add_u64 v[200:201], v[6:7], 0, s[26:27]
	global_load_dword v128, v[198:199], off offset:1024
	global_load_dword v129, v[200:201], off offset:1024
	s_mov_b32 s26, 0x1000
	s_mov_b32 s27, 0
	v_lshl_add_u64 v[198:199], v[6:7], 0, s[26:27]
	s_mov_b32 s26, 0x11000
	v_lshl_add_u64 v[200:201], v[6:7], 0, s[26:27]
	global_load_dword v130, v[198:199], off offset:2048
	global_load_dword v131, v[200:201], off offset:2048
	s_mov_b32 s26, 0x1000
	s_mov_b32 s27, 0
	v_lshl_add_u64 v[198:199], v[6:7], 0, s[26:27]
	s_mov_b32 s26, 0x11000
	v_lshl_add_u64 v[200:201], v[6:7], 0, s[26:27]
	global_load_dword v132, v[198:199], off offset:3072
	global_load_dword v133, v[200:201], off offset:3072
	s_mov_b32 s26, 0x2000
	s_mov_b32 s27, 0
	v_lshl_add_u64 v[198:199], v[6:7], 0, s[26:27]
	s_mov_b32 s26, 0x12000
	v_lshl_add_u64 v[200:201], v[6:7], 0, s[26:27]
	global_load_dword v134, v[198:199], off
	global_load_dword v135, v[200:201], off
	s_mov_b32 s26, 0x2000
	s_mov_b32 s27, 0
	v_lshl_add_u64 v[198:199], v[6:7], 0, s[26:27]
	s_mov_b32 s26, 0x12000
	v_lshl_add_u64 v[200:201], v[6:7], 0, s[26:27]
	global_load_dword v136, v[198:199], off offset:1024
	global_load_dword v137, v[200:201], off offset:1024
	s_mov_b32 s26, 0x2000
	s_mov_b32 s27, 0
	v_lshl_add_u64 v[198:199], v[6:7], 0, s[26:27]
	s_mov_b32 s26, 0x12000
	v_lshl_add_u64 v[200:201], v[6:7], 0, s[26:27]
	global_load_dword v138, v[198:199], off offset:2048
	global_load_dword v139, v[200:201], off offset:2048
	s_mov_b32 s26, 0x2000
	s_mov_b32 s27, 0
	v_lshl_add_u64 v[198:199], v[6:7], 0, s[26:27]
	s_mov_b32 s26, 0x12000
	v_lshl_add_u64 v[200:201], v[6:7], 0, s[26:27]
	global_load_dword v140, v[198:199], off offset:3072
	global_load_dword v141, v[200:201], off offset:3072
	s_mov_b32 s26, 0x3000
	s_mov_b32 s27, 0
	v_lshl_add_u64 v[198:199], v[6:7], 0, s[26:27]
	s_mov_b32 s26, 0x13000
	v_lshl_add_u64 v[200:201], v[6:7], 0, s[26:27]
	global_load_dword v142, v[198:199], off
	global_load_dword v143, v[200:201], off
	s_mov_b32 s26, 0x3000
	s_mov_b32 s27, 0
	v_lshl_add_u64 v[198:199], v[6:7], 0, s[26:27]
	s_mov_b32 s26, 0x13000
	v_lshl_add_u64 v[200:201], v[6:7], 0, s[26:27]
	global_load_dword v144, v[198:199], off offset:1024
	global_load_dword v145, v[200:201], off offset:1024
	s_mov_b32 s26, 0x3000
	s_mov_b32 s27, 0
	v_lshl_add_u64 v[198:199], v[6:7], 0, s[26:27]
	s_mov_b32 s26, 0x13000
	v_lshl_add_u64 v[200:201], v[6:7], 0, s[26:27]
	global_load_dword v146, v[198:199], off offset:2048
	global_load_dword v147, v[200:201], off offset:2048
	s_mov_b32 s26, 0x3000
	s_mov_b32 s27, 0
	v_lshl_add_u64 v[198:199], v[6:7], 0, s[26:27]
	s_mov_b32 s26, 0x13000
	v_lshl_add_u64 v[200:201], v[6:7], 0, s[26:27]
	global_load_dword v148, v[198:199], off offset:3072
	global_load_dword v149, v[200:201], off offset:3072
	s_mov_b32 s26, 0x4000
	s_mov_b32 s27, 0
	v_lshl_add_u64 v[198:199], v[6:7], 0, s[26:27]
	s_mov_b32 s26, 0x14000
	v_lshl_add_u64 v[200:201], v[6:7], 0, s[26:27]
	global_load_dword v166, v[198:199], off
	global_load_dword v167, v[200:201], off
	s_mov_b32 s26, 0x4000
	s_mov_b32 s27, 0
	v_lshl_add_u64 v[198:199], v[6:7], 0, s[26:27]
	s_mov_b32 s26, 0x14000
	v_lshl_add_u64 v[200:201], v[6:7], 0, s[26:27]
	global_load_dword v168, v[198:199], off offset:1024
	global_load_dword v169, v[200:201], off offset:1024
	s_mov_b32 s26, 0x4000
	s_mov_b32 s27, 0
	v_lshl_add_u64 v[198:199], v[6:7], 0, s[26:27]
	s_mov_b32 s26, 0x14000
	v_lshl_add_u64 v[200:201], v[6:7], 0, s[26:27]
	global_load_dword v170, v[198:199], off offset:2048
	global_load_dword v171, v[200:201], off offset:2048
	s_mov_b32 s26, 0x4000
	s_mov_b32 s27, 0
	v_lshl_add_u64 v[198:199], v[6:7], 0, s[26:27]
	s_mov_b32 s26, 0x14000
	v_lshl_add_u64 v[200:201], v[6:7], 0, s[26:27]
	global_load_dword v172, v[198:199], off offset:3072
	global_load_dword v173, v[200:201], off offset:3072
	s_mov_b32 s26, 0x5000
	s_mov_b32 s27, 0
	v_lshl_add_u64 v[198:199], v[6:7], 0, s[26:27]
	s_mov_b32 s26, 0x15000
	v_lshl_add_u64 v[200:201], v[6:7], 0, s[26:27]
	global_load_dword v174, v[198:199], off
	global_load_dword v175, v[200:201], off
	s_mov_b32 s26, 0x5000
	s_mov_b32 s27, 0
	v_lshl_add_u64 v[198:199], v[6:7], 0, s[26:27]
	s_mov_b32 s26, 0x15000
	v_lshl_add_u64 v[200:201], v[6:7], 0, s[26:27]
	global_load_dword v176, v[198:199], off offset:1024
	global_load_dword v177, v[200:201], off offset:1024
	s_mov_b32 s26, 0x5000
	s_mov_b32 s27, 0
	v_lshl_add_u64 v[198:199], v[6:7], 0, s[26:27]
	s_mov_b32 s26, 0x15000
	v_lshl_add_u64 v[200:201], v[6:7], 0, s[26:27]
	global_load_dword v178, v[198:199], off offset:2048
	global_load_dword v179, v[200:201], off offset:2048
	s_mov_b32 s26, 0x5000
	s_mov_b32 s27, 0
	v_lshl_add_u64 v[198:199], v[6:7], 0, s[26:27]
	s_mov_b32 s26, 0x15000
	v_lshl_add_u64 v[200:201], v[6:7], 0, s[26:27]
	global_load_dword v180, v[198:199], off offset:3072
	global_load_dword v181, v[200:201], off offset:3072
	s_mov_b32 s26, 0x6000
	s_mov_b32 s27, 0
	v_lshl_add_u64 v[198:199], v[6:7], 0, s[26:27]
	s_mov_b32 s26, 0x16000
	v_lshl_add_u64 v[200:201], v[6:7], 0, s[26:27]
	global_load_dword v182, v[198:199], off
	global_load_dword v183, v[200:201], off
	s_mov_b32 s26, 0x6000
	s_mov_b32 s27, 0
	v_lshl_add_u64 v[198:199], v[6:7], 0, s[26:27]
	s_mov_b32 s26, 0x16000
	v_lshl_add_u64 v[200:201], v[6:7], 0, s[26:27]
	global_load_dword v184, v[198:199], off offset:1024
	global_load_dword v185, v[200:201], off offset:1024
	s_mov_b32 s26, 0x6000
	s_mov_b32 s27, 0
	v_lshl_add_u64 v[198:199], v[6:7], 0, s[26:27]
	s_mov_b32 s26, 0x16000
	v_lshl_add_u64 v[200:201], v[6:7], 0, s[26:27]
	global_load_dword v186, v[198:199], off offset:2048
	global_load_dword v187, v[200:201], off offset:2048
	s_mov_b32 s26, 0x6000
	s_mov_b32 s27, 0
	v_lshl_add_u64 v[198:199], v[6:7], 0, s[26:27]
	s_mov_b32 s26, 0x16000
	v_lshl_add_u64 v[200:201], v[6:7], 0, s[26:27]
	global_load_dword v188, v[198:199], off offset:3072
	global_load_dword v189, v[200:201], off offset:3072
	s_mov_b32 s26, 0x7000
	s_mov_b32 s27, 0
	v_lshl_add_u64 v[198:199], v[6:7], 0, s[26:27]
	s_mov_b32 s26, 0x17000
	v_lshl_add_u64 v[200:201], v[6:7], 0, s[26:27]
	global_load_dword v190, v[198:199], off
	global_load_dword v191, v[200:201], off
	s_mov_b32 s26, 0x7000
	s_mov_b32 s27, 0
	v_lshl_add_u64 v[198:199], v[6:7], 0, s[26:27]
	s_mov_b32 s26, 0x17000
	v_lshl_add_u64 v[200:201], v[6:7], 0, s[26:27]
	global_load_dword v192, v[198:199], off offset:1024
	global_load_dword v193, v[200:201], off offset:1024
	v_readlane_b32 s40, v13, 0
	v_readlane_b32 s41, v13, 1
	v_readlane_b32 s42, v13, 2
	v_readlane_b32 s43, v13, 3
	v_readlane_b32 s44, v14, 0
	v_readlane_b32 s45, v14, 1
	v_readlane_b32 s46, v14, 2
	v_readlane_b32 s47, v14, 3
	s_waitcnt vmcnt(58)
	v_fmac_f32_e32 v8, s40, v118
	v_fmac_f32_e32 v8, s44, v119
	s_mov_b32 s26, 0x7000
	s_mov_b32 s27, 0
	v_lshl_add_u64 v[198:199], v[6:7], 0, s[26:27]
	s_mov_b32 s26, 0x17000
	v_lshl_add_u64 v[200:201], v[6:7], 0, s[26:27]
	global_load_dword v118, v[198:199], off offset:2048
	global_load_dword v119, v[200:201], off offset:2048
	s_waitcnt vmcnt(58)
	v_fmac_f32_e32 v8, s41, v120
	v_fmac_f32_e32 v8, s45, v121
	s_mov_b32 s26, 0x7000
	s_mov_b32 s27, 0
	v_lshl_add_u64 v[198:199], v[6:7], 0, s[26:27]
	s_mov_b32 s26, 0x17000
	v_lshl_add_u64 v[200:201], v[6:7], 0, s[26:27]
	global_load_dword v120, v[198:199], off offset:3072
	global_load_dword v121, v[200:201], off offset:3072
	s_waitcnt vmcnt(58)
	v_fmac_f32_e32 v8, s42, v122
	v_fmac_f32_e32 v8, s46, v123
	s_mov_b32 s26, 0x8000
	s_mov_b32 s27, 0
	v_lshl_add_u64 v[198:199], v[6:7], 0, s[26:27]
	s_mov_b32 s26, 0x18000
	v_lshl_add_u64 v[200:201], v[6:7], 0, s[26:27]
	global_load_dword v122, v[198:199], off
	global_load_dword v123, v[200:201], off
	s_waitcnt vmcnt(58)
	v_fmac_f32_e32 v8, s43, v124
	v_fmac_f32_e32 v8, s47, v125
	s_mov_b32 s26, 0x8000
	s_mov_b32 s27, 0
	v_lshl_add_u64 v[198:199], v[6:7], 0, s[26:27]
	s_mov_b32 s26, 0x18000
	v_lshl_add_u64 v[200:201], v[6:7], 0, s[26:27]
	global_load_dword v124, v[198:199], off offset:1024
	global_load_dword v125, v[200:201], off offset:1024
	v_readlane_b32 s40, v13, 4
	v_readlane_b32 s41, v13, 5
	v_readlane_b32 s42, v13, 6
	v_readlane_b32 s43, v13, 7
	v_readlane_b32 s44, v14, 4
	v_readlane_b32 s45, v14, 5
	v_readlane_b32 s46, v14, 6
	v_readlane_b32 s47, v14, 7
	s_waitcnt vmcnt(58)
	v_fmac_f32_e32 v8, s40, v126
	v_fmac_f32_e32 v8, s44, v127
	s_mov_b32 s26, 0x8000
	s_mov_b32 s27, 0
	v_lshl_add_u64 v[198:199], v[6:7], 0, s[26:27]
	s_mov_b32 s26, 0x18000
	v_lshl_add_u64 v[200:201], v[6:7], 0, s[26:27]
	global_load_dword v126, v[198:199], off offset:2048
	global_load_dword v127, v[200:201], off offset:2048
	s_waitcnt vmcnt(58)
	v_fmac_f32_e32 v8, s41, v128
	v_fmac_f32_e32 v8, s45, v129
	s_mov_b32 s26, 0x8000
	s_mov_b32 s27, 0
	v_lshl_add_u64 v[198:199], v[6:7], 0, s[26:27]
	s_mov_b32 s26, 0x18000
	v_lshl_add_u64 v[200:201], v[6:7], 0, s[26:27]
	global_load_dword v128, v[198:199], off offset:3072
	global_load_dword v129, v[200:201], off offset:3072
	s_waitcnt vmcnt(58)
	v_fmac_f32_e32 v8, s42, v130
	v_fmac_f32_e32 v8, s46, v131
	s_mov_b32 s26, 0x9000
	s_mov_b32 s27, 0
	v_lshl_add_u64 v[198:199], v[6:7], 0, s[26:27]
	s_mov_b32 s26, 0x19000
	v_lshl_add_u64 v[200:201], v[6:7], 0, s[26:27]
	global_load_dword v130, v[198:199], off
	global_load_dword v131, v[200:201], off
	s_waitcnt vmcnt(58)
	v_fmac_f32_e32 v8, s43, v132
	v_fmac_f32_e32 v8, s47, v133
	s_mov_b32 s26, 0x9000
	s_mov_b32 s27, 0
	v_lshl_add_u64 v[198:199], v[6:7], 0, s[26:27]
	s_mov_b32 s26, 0x19000
	v_lshl_add_u64 v[200:201], v[6:7], 0, s[26:27]
	global_load_dword v132, v[198:199], off offset:1024
	global_load_dword v133, v[200:201], off offset:1024
	v_readlane_b32 s40, v13, 8
	v_readlane_b32 s41, v13, 9
	v_readlane_b32 s42, v13, 10
	v_readlane_b32 s43, v13, 11
	v_readlane_b32 s44, v14, 8
	v_readlane_b32 s45, v14, 9
	v_readlane_b32 s46, v14, 10
	v_readlane_b32 s47, v14, 11
	s_waitcnt vmcnt(58)
	v_fmac_f32_e32 v8, s40, v134
	v_fmac_f32_e32 v8, s44, v135
	s_mov_b32 s26, 0x9000
	s_mov_b32 s27, 0
	v_lshl_add_u64 v[198:199], v[6:7], 0, s[26:27]
	s_mov_b32 s26, 0x19000
	v_lshl_add_u64 v[200:201], v[6:7], 0, s[26:27]
	global_load_dword v134, v[198:199], off offset:2048
	global_load_dword v135, v[200:201], off offset:2048
	s_waitcnt vmcnt(58)
	v_fmac_f32_e32 v8, s41, v136
	v_fmac_f32_e32 v8, s45, v137
	s_mov_b32 s26, 0x9000
	s_mov_b32 s27, 0
	v_lshl_add_u64 v[198:199], v[6:7], 0, s[26:27]
	s_mov_b32 s26, 0x19000
	v_lshl_add_u64 v[200:201], v[6:7], 0, s[26:27]
	global_load_dword v136, v[198:199], off offset:3072
	global_load_dword v137, v[200:201], off offset:3072
	s_waitcnt vmcnt(58)
	v_fmac_f32_e32 v8, s42, v138
	v_fmac_f32_e32 v8, s46, v139
	s_mov_b32 s26, 0xa000
	s_mov_b32 s27, 0
	v_lshl_add_u64 v[198:199], v[6:7], 0, s[26:27]
	s_mov_b32 s26, 0x1a000
	v_lshl_add_u64 v[200:201], v[6:7], 0, s[26:27]
	global_load_dword v138, v[198:199], off
	global_load_dword v139, v[200:201], off
	s_waitcnt vmcnt(58)
	v_fmac_f32_e32 v8, s43, v140
	v_fmac_f32_e32 v8, s47, v141
	s_mov_b32 s26, 0xa000
	s_mov_b32 s27, 0
	v_lshl_add_u64 v[198:199], v[6:7], 0, s[26:27]
	s_mov_b32 s26, 0x1a000
	v_lshl_add_u64 v[200:201], v[6:7], 0, s[26:27]
	global_load_dword v140, v[198:199], off offset:1024
	global_load_dword v141, v[200:201], off offset:1024
	v_readlane_b32 s40, v13, 12
	v_readlane_b32 s41, v13, 13
	v_readlane_b32 s42, v13, 14
	v_readlane_b32 s43, v13, 15
	v_readlane_b32 s44, v14, 12
	v_readlane_b32 s45, v14, 13
	v_readlane_b32 s46, v14, 14
	v_readlane_b32 s47, v14, 15
	s_waitcnt vmcnt(58)
	v_fmac_f32_e32 v8, s40, v142
	v_fmac_f32_e32 v8, s44, v143
	s_mov_b32 s26, 0xa000
	s_mov_b32 s27, 0
	v_lshl_add_u64 v[198:199], v[6:7], 0, s[26:27]
	s_mov_b32 s26, 0x1a000
	v_lshl_add_u64 v[200:201], v[6:7], 0, s[26:27]
	global_load_dword v142, v[198:199], off offset:2048
	global_load_dword v143, v[200:201], off offset:2048
	s_waitcnt vmcnt(58)
	v_fmac_f32_e32 v8, s41, v144
	v_fmac_f32_e32 v8, s45, v145
	s_mov_b32 s26, 0xa000
	s_mov_b32 s27, 0
	v_lshl_add_u64 v[198:199], v[6:7], 0, s[26:27]
	s_mov_b32 s26, 0x1a000
	v_lshl_add_u64 v[200:201], v[6:7], 0, s[26:27]
	global_load_dword v144, v[198:199], off offset:3072
	global_load_dword v145, v[200:201], off offset:3072
	s_waitcnt vmcnt(58)
	v_fmac_f32_e32 v8, s42, v146
	v_fmac_f32_e32 v8, s46, v147
	s_mov_b32 s26, 0xb000
	s_mov_b32 s27, 0
	v_lshl_add_u64 v[198:199], v[6:7], 0, s[26:27]
	s_mov_b32 s26, 0x1b000
	v_lshl_add_u64 v[200:201], v[6:7], 0, s[26:27]
	global_load_dword v146, v[198:199], off
	global_load_dword v147, v[200:201], off
	s_waitcnt vmcnt(58)
	v_fmac_f32_e32 v8, s43, v148
	v_fmac_f32_e32 v8, s47, v149
	s_mov_b32 s26, 0xb000
	s_mov_b32 s27, 0
	v_lshl_add_u64 v[198:199], v[6:7], 0, s[26:27]
	s_mov_b32 s26, 0x1b000
	v_lshl_add_u64 v[200:201], v[6:7], 0, s[26:27]
	global_load_dword v148, v[198:199], off offset:1024
	global_load_dword v149, v[200:201], off offset:1024
	v_readlane_b32 s40, v13, 16
	v_readlane_b32 s41, v13, 17
	v_readlane_b32 s42, v13, 18
	v_readlane_b32 s43, v13, 19
	v_readlane_b32 s44, v14, 16
	v_readlane_b32 s45, v14, 17
	v_readlane_b32 s46, v14, 18
	v_readlane_b32 s47, v14, 19
	s_waitcnt vmcnt(58)
	v_fmac_f32_e32 v8, s40, v166
	v_fmac_f32_e32 v8, s44, v167
	s_mov_b32 s26, 0xb000
	s_mov_b32 s27, 0
	v_lshl_add_u64 v[198:199], v[6:7], 0, s[26:27]
	s_mov_b32 s26, 0x1b000
	v_lshl_add_u64 v[200:201], v[6:7], 0, s[26:27]
	global_load_dword v166, v[198:199], off offset:2048
	global_load_dword v167, v[200:201], off offset:2048
	s_waitcnt vmcnt(58)
	v_fmac_f32_e32 v8, s41, v168
	v_fmac_f32_e32 v8, s45, v169
	s_mov_b32 s26, 0xb000
	s_mov_b32 s27, 0
	v_lshl_add_u64 v[198:199], v[6:7], 0, s[26:27]
	s_mov_b32 s26, 0x1b000
	v_lshl_add_u64 v[200:201], v[6:7], 0, s[26:27]
	global_load_dword v168, v[198:199], off offset:3072
	global_load_dword v169, v[200:201], off offset:3072
	s_waitcnt vmcnt(58)
	v_fmac_f32_e32 v8, s42, v170
	v_fmac_f32_e32 v8, s46, v171
	s_mov_b32 s26, 0xc000
	s_mov_b32 s27, 0
	v_lshl_add_u64 v[198:199], v[6:7], 0, s[26:27]
	s_mov_b32 s26, 0x1c000
	v_lshl_add_u64 v[200:201], v[6:7], 0, s[26:27]
	global_load_dword v170, v[198:199], off
	global_load_dword v171, v[200:201], off
	s_waitcnt vmcnt(58)
	v_fmac_f32_e32 v8, s43, v172
	v_fmac_f32_e32 v8, s47, v173
	s_mov_b32 s26, 0xc000
	s_mov_b32 s27, 0
	v_lshl_add_u64 v[198:199], v[6:7], 0, s[26:27]
	s_mov_b32 s26, 0x1c000
	v_lshl_add_u64 v[200:201], v[6:7], 0, s[26:27]
	global_load_dword v172, v[198:199], off offset:1024
	global_load_dword v173, v[200:201], off offset:1024
	v_readlane_b32 s40, v13, 20
	v_readlane_b32 s41, v13, 21
	v_readlane_b32 s42, v13, 22
	v_readlane_b32 s43, v13, 23
	v_readlane_b32 s44, v14, 20
	v_readlane_b32 s45, v14, 21
	v_readlane_b32 s46, v14, 22
	v_readlane_b32 s47, v14, 23
	s_waitcnt vmcnt(58)
	v_fmac_f32_e32 v8, s40, v174
	v_fmac_f32_e32 v8, s44, v175
	s_mov_b32 s26, 0xc000
	s_mov_b32 s27, 0
	v_lshl_add_u64 v[198:199], v[6:7], 0, s[26:27]
	s_mov_b32 s26, 0x1c000
	v_lshl_add_u64 v[200:201], v[6:7], 0, s[26:27]
	global_load_dword v174, v[198:199], off offset:2048
	global_load_dword v175, v[200:201], off offset:2048
	s_waitcnt vmcnt(58)
	v_fmac_f32_e32 v8, s41, v176
	v_fmac_f32_e32 v8, s45, v177
	s_mov_b32 s26, 0xc000
	s_mov_b32 s27, 0
	v_lshl_add_u64 v[198:199], v[6:7], 0, s[26:27]
	s_mov_b32 s26, 0x1c000
	v_lshl_add_u64 v[200:201], v[6:7], 0, s[26:27]
	global_load_dword v176, v[198:199], off offset:3072
	global_load_dword v177, v[200:201], off offset:3072
	s_waitcnt vmcnt(58)
	v_fmac_f32_e32 v8, s42, v178
	v_fmac_f32_e32 v8, s46, v179
	s_mov_b32 s26, 0xd000
	s_mov_b32 s27, 0
	v_lshl_add_u64 v[198:199], v[6:7], 0, s[26:27]
	s_mov_b32 s26, 0x1d000
	v_lshl_add_u64 v[200:201], v[6:7], 0, s[26:27]
	global_load_dword v178, v[198:199], off
	global_load_dword v179, v[200:201], off
	s_waitcnt vmcnt(58)
	v_fmac_f32_e32 v8, s43, v180
	v_fmac_f32_e32 v8, s47, v181
	s_mov_b32 s26, 0xd000
	s_mov_b32 s27, 0
	v_lshl_add_u64 v[198:199], v[6:7], 0, s[26:27]
	s_mov_b32 s26, 0x1d000
	v_lshl_add_u64 v[200:201], v[6:7], 0, s[26:27]
	global_load_dword v180, v[198:199], off offset:1024
	global_load_dword v181, v[200:201], off offset:1024
	v_readlane_b32 s40, v13, 24
	v_readlane_b32 s41, v13, 25
	v_readlane_b32 s42, v13, 26
	v_readlane_b32 s43, v13, 27
	v_readlane_b32 s44, v14, 24
	v_readlane_b32 s45, v14, 25
	v_readlane_b32 s46, v14, 26
	v_readlane_b32 s47, v14, 27
	s_waitcnt vmcnt(58)
	v_fmac_f32_e32 v8, s40, v182
	v_fmac_f32_e32 v8, s44, v183
	s_mov_b32 s26, 0xd000
	s_mov_b32 s27, 0
	v_lshl_add_u64 v[198:199], v[6:7], 0, s[26:27]
	s_mov_b32 s26, 0x1d000
	v_lshl_add_u64 v[200:201], v[6:7], 0, s[26:27]
	global_load_dword v182, v[198:199], off offset:2048
	global_load_dword v183, v[200:201], off offset:2048
	s_waitcnt vmcnt(58)
	v_fmac_f32_e32 v8, s41, v184
	v_fmac_f32_e32 v8, s45, v185
	s_mov_b32 s26, 0xd000
	s_mov_b32 s27, 0
	v_lshl_add_u64 v[198:199], v[6:7], 0, s[26:27]
	s_mov_b32 s26, 0x1d000
	v_lshl_add_u64 v[200:201], v[6:7], 0, s[26:27]
	global_load_dword v184, v[198:199], off offset:3072
	global_load_dword v185, v[200:201], off offset:3072
	s_waitcnt vmcnt(58)
	v_fmac_f32_e32 v8, s42, v186
	v_fmac_f32_e32 v8, s46, v187
	s_mov_b32 s26, 0xe000
	s_mov_b32 s27, 0
	v_lshl_add_u64 v[198:199], v[6:7], 0, s[26:27]
	s_mov_b32 s26, 0x1e000
	v_lshl_add_u64 v[200:201], v[6:7], 0, s[26:27]
	global_load_dword v186, v[198:199], off
	global_load_dword v187, v[200:201], off
	s_waitcnt vmcnt(58)
	v_fmac_f32_e32 v8, s43, v188
	v_fmac_f32_e32 v8, s47, v189
	s_mov_b32 s26, 0xe000
	s_mov_b32 s27, 0
	v_lshl_add_u64 v[198:199], v[6:7], 0, s[26:27]
	s_mov_b32 s26, 0x1e000
	v_lshl_add_u64 v[200:201], v[6:7], 0, s[26:27]
	global_load_dword v188, v[198:199], off offset:1024
	global_load_dword v189, v[200:201], off offset:1024
	v_readlane_b32 s40, v13, 28
	v_readlane_b32 s41, v13, 29
	v_readlane_b32 s42, v13, 30
	v_readlane_b32 s43, v13, 31
	v_readlane_b32 s44, v14, 28
	v_readlane_b32 s45, v14, 29
	v_readlane_b32 s46, v14, 30
	v_readlane_b32 s47, v14, 31
	s_waitcnt vmcnt(58)
	v_fmac_f32_e32 v8, s40, v190
	v_fmac_f32_e32 v8, s44, v191
	s_mov_b32 s26, 0xe000
	s_mov_b32 s27, 0
	v_lshl_add_u64 v[198:199], v[6:7], 0, s[26:27]
	s_mov_b32 s26, 0x1e000
	v_lshl_add_u64 v[200:201], v[6:7], 0, s[26:27]
	global_load_dword v190, v[198:199], off offset:2048
	global_load_dword v191, v[200:201], off offset:2048
	s_waitcnt vmcnt(58)
	v_fmac_f32_e32 v8, s41, v192
	v_fmac_f32_e32 v8, s45, v193
	s_mov_b32 s26, 0xe000
	s_mov_b32 s27, 0
	v_lshl_add_u64 v[198:199], v[6:7], 0, s[26:27]
	s_mov_b32 s26, 0x1e000
	v_lshl_add_u64 v[200:201], v[6:7], 0, s[26:27]
	global_load_dword v192, v[198:199], off offset:3072
	global_load_dword v193, v[200:201], off offset:3072
	s_waitcnt vmcnt(58)
	v_fmac_f32_e32 v8, s42, v118
	v_fmac_f32_e32 v8, s46, v119
	s_mov_b32 s26, 0xf000
	s_mov_b32 s27, 0
	v_lshl_add_u64 v[198:199], v[6:7], 0, s[26:27]
	s_mov_b32 s26, 0x1f000
	v_lshl_add_u64 v[200:201], v[6:7], 0, s[26:27]
	global_load_dword v118, v[198:199], off
	global_load_dword v119, v[200:201], off
	s_waitcnt vmcnt(58)
	v_fmac_f32_e32 v8, s43, v120
	v_fmac_f32_e32 v8, s47, v121
	s_mov_b32 s26, 0xf000
	s_mov_b32 s27, 0
	v_lshl_add_u64 v[198:199], v[6:7], 0, s[26:27]
	s_mov_b32 s26, 0x1f000
	v_lshl_add_u64 v[200:201], v[6:7], 0, s[26:27]
	global_load_dword v120, v[198:199], off offset:1024
	global_load_dword v121, v[200:201], off offset:1024
	v_readlane_b32 s40, v13, 32
	v_readlane_b32 s41, v13, 33
	v_readlane_b32 s42, v13, 34
	v_readlane_b32 s43, v13, 35
	v_readlane_b32 s44, v14, 32
	v_readlane_b32 s45, v14, 33
	v_readlane_b32 s46, v14, 34
	v_readlane_b32 s47, v14, 35
	s_waitcnt vmcnt(58)
	v_fmac_f32_e32 v8, s40, v122
	v_fmac_f32_e32 v8, s44, v123
	s_mov_b32 s26, 0xf000
	s_mov_b32 s27, 0
	v_lshl_add_u64 v[198:199], v[6:7], 0, s[26:27]
	s_mov_b32 s26, 0x1f000
	v_lshl_add_u64 v[200:201], v[6:7], 0, s[26:27]
	global_load_dword v122, v[198:199], off offset:2048
	global_load_dword v123, v[200:201], off offset:2048
	s_waitcnt vmcnt(58)
	v_fmac_f32_e32 v8, s41, v124
	v_fmac_f32_e32 v8, s45, v125
	s_mov_b32 s26, 0xf000
	s_mov_b32 s27, 0
	v_lshl_add_u64 v[198:199], v[6:7], 0, s[26:27]
	s_mov_b32 s26, 0x1f000
	v_lshl_add_u64 v[200:201], v[6:7], 0, s[26:27]
	global_load_dword v124, v[198:199], off offset:3072
	global_load_dword v125, v[200:201], off offset:3072
	s_waitcnt vmcnt(58)
	v_fmac_f32_e32 v8, s42, v126
	v_fmac_f32_e32 v8, s46, v127
	s_waitcnt vmcnt(56)
	v_fmac_f32_e32 v8, s43, v128
	v_fmac_f32_e32 v8, s47, v129
	v_readlane_b32 s40, v13, 36
	v_readlane_b32 s41, v13, 37
	v_readlane_b32 s42, v13, 38
	v_readlane_b32 s43, v13, 39
	v_readlane_b32 s44, v14, 36
	v_readlane_b32 s45, v14, 37
	v_readlane_b32 s46, v14, 38
	v_readlane_b32 s47, v14, 39
	s_waitcnt vmcnt(54)
	v_fmac_f32_e32 v8, s40, v130
	v_fmac_f32_e32 v8, s44, v131
	s_waitcnt vmcnt(52)
	v_fmac_f32_e32 v8, s41, v132
	v_fmac_f32_e32 v8, s45, v133
	s_waitcnt vmcnt(50)
	v_fmac_f32_e32 v8, s42, v134
	v_fmac_f32_e32 v8, s46, v135
	s_waitcnt vmcnt(48)
	v_fmac_f32_e32 v8, s43, v136
	v_fmac_f32_e32 v8, s47, v137
	v_readlane_b32 s40, v13, 40
	v_readlane_b32 s41, v13, 41
	v_readlane_b32 s42, v13, 42
	v_readlane_b32 s43, v13, 43
	v_readlane_b32 s44, v14, 40
	v_readlane_b32 s45, v14, 41
	v_readlane_b32 s46, v14, 42
	v_readlane_b32 s47, v14, 43
	s_waitcnt vmcnt(46)
	v_fmac_f32_e32 v8, s40, v138
	v_fmac_f32_e32 v8, s44, v139
	s_waitcnt vmcnt(44)
	v_fmac_f32_e32 v8, s41, v140
	v_fmac_f32_e32 v8, s45, v141
	s_waitcnt vmcnt(42)
	v_fmac_f32_e32 v8, s42, v142
	v_fmac_f32_e32 v8, s46, v143
	s_waitcnt vmcnt(40)
	v_fmac_f32_e32 v8, s43, v144
	v_fmac_f32_e32 v8, s47, v145
	v_readlane_b32 s40, v13, 44
	v_readlane_b32 s41, v13, 45
	v_readlane_b32 s42, v13, 46
	v_readlane_b32 s43, v13, 47
	v_readlane_b32 s44, v14, 44
	v_readlane_b32 s45, v14, 45
	v_readlane_b32 s46, v14, 46
	v_readlane_b32 s47, v14, 47
	s_waitcnt vmcnt(38)
	v_fmac_f32_e32 v8, s40, v146
	v_fmac_f32_e32 v8, s44, v147
	s_waitcnt vmcnt(36)
	v_fmac_f32_e32 v8, s41, v148
	v_fmac_f32_e32 v8, s45, v149
	s_waitcnt vmcnt(34)
	v_fmac_f32_e32 v8, s42, v166
	v_fmac_f32_e32 v8, s46, v167
	s_waitcnt vmcnt(32)
	v_fmac_f32_e32 v8, s43, v168
	v_fmac_f32_e32 v8, s47, v169
	v_readlane_b32 s40, v13, 48
	v_readlane_b32 s41, v13, 49
	v_readlane_b32 s42, v13, 50
	v_readlane_b32 s43, v13, 51
	v_readlane_b32 s44, v14, 48
	v_readlane_b32 s45, v14, 49
	v_readlane_b32 s46, v14, 50
	v_readlane_b32 s47, v14, 51
	s_waitcnt vmcnt(30)
	v_fmac_f32_e32 v8, s40, v170
	v_fmac_f32_e32 v8, s44, v171
	s_waitcnt vmcnt(28)
	v_fmac_f32_e32 v8, s41, v172
	v_fmac_f32_e32 v8, s45, v173
	s_waitcnt vmcnt(26)
	v_fmac_f32_e32 v8, s42, v174
	v_fmac_f32_e32 v8, s46, v175
	s_waitcnt vmcnt(24)
	v_fmac_f32_e32 v8, s43, v176
	v_fmac_f32_e32 v8, s47, v177
	v_readlane_b32 s40, v13, 52
	v_readlane_b32 s41, v13, 53
	v_readlane_b32 s42, v13, 54
	v_readlane_b32 s43, v13, 55
	v_readlane_b32 s44, v14, 52
	v_readlane_b32 s45, v14, 53
	v_readlane_b32 s46, v14, 54
	v_readlane_b32 s47, v14, 55
	s_waitcnt vmcnt(22)
	v_fmac_f32_e32 v8, s40, v178
	v_fmac_f32_e32 v8, s44, v179
	s_waitcnt vmcnt(20)
	v_fmac_f32_e32 v8, s41, v180
	v_fmac_f32_e32 v8, s45, v181
	s_waitcnt vmcnt(18)
	v_fmac_f32_e32 v8, s42, v182
	v_fmac_f32_e32 v8, s46, v183
	s_waitcnt vmcnt(16)
	v_fmac_f32_e32 v8, s43, v184
	v_fmac_f32_e32 v8, s47, v185
	v_readlane_b32 s40, v13, 56
	v_readlane_b32 s41, v13, 57
	v_readlane_b32 s42, v13, 58
	v_readlane_b32 s43, v13, 59
	v_readlane_b32 s44, v14, 56
	v_readlane_b32 s45, v14, 57
	v_readlane_b32 s46, v14, 58
	v_readlane_b32 s47, v14, 59
	s_waitcnt vmcnt(14)
	v_fmac_f32_e32 v8, s40, v186
	v_fmac_f32_e32 v8, s44, v187
	s_waitcnt vmcnt(12)
	v_fmac_f32_e32 v8, s41, v188
	v_fmac_f32_e32 v8, s45, v189
	s_waitcnt vmcnt(10)
	v_fmac_f32_e32 v8, s42, v190
	v_fmac_f32_e32 v8, s46, v191
	s_waitcnt vmcnt(8)
	v_fmac_f32_e32 v8, s43, v192
	v_fmac_f32_e32 v8, s47, v193
	v_readlane_b32 s40, v13, 60
	v_readlane_b32 s41, v13, 61
	v_readlane_b32 s42, v13, 62
	v_readlane_b32 s43, v13, 63
	v_readlane_b32 s44, v14, 60
	v_readlane_b32 s45, v14, 61
	v_readlane_b32 s46, v14, 62
	v_readlane_b32 s47, v14, 63
	s_waitcnt vmcnt(6)
	v_fmac_f32_e32 v8, s40, v118
	v_fmac_f32_e32 v8, s44, v119
	s_waitcnt vmcnt(4)
	v_fmac_f32_e32 v8, s41, v120
	v_fmac_f32_e32 v8, s45, v121
	s_waitcnt vmcnt(2)
	v_fmac_f32_e32 v8, s42, v122
	v_fmac_f32_e32 v8, s46, v123
	s_waitcnt vmcnt(0)
	v_fmac_f32_e32 v8, s43, v124
	v_fmac_f32_e32 v8, s47, v125
	v_add_f32_e32 v6, v15, v17
	ds_bpermute_b32 v7, v79, v6
	v_sub_f32_e32 v12, v16, v12
	v_mul_f32_e32 v12, 0x3fb8aa3b, v12
	v_exp_f32_e32 v12, v12
	s_lshl_b64 s[2:3], s[4:5], 12
	s_waitcnt lgkmcnt(0)
	v_add_f32_e32 v6, v6, v7
	ds_bpermute_b32 v7, v80, v6
	s_add_u32 s4, s19, s2
	s_addc_u32 s5, s18, s3
	s_waitcnt lgkmcnt(0)
	v_add_f32_e32 v6, v6, v7
	v_add_f32_e32 v6, v9, v6
	v_add_f32_e32 v6, v12, v6
	v_div_scale_f32 v7, s[2:3], v6, v6, v8
	v_rcp_f32_e32 v9, v7
	v_div_scale_f32 v12, vcc, v8, v6, v8
	s_lshl_b32 s2, s23, 1
	v_fma_f32 v13, -v7, v9, 1.0
	v_fmac_f32_e32 v9, v13, v9
	v_mul_f32_e32 v13, v12, v9
	v_fma_f32 v14, -v7, v13, v12
	v_fmac_f32_e32 v13, v14, v9
	v_fma_f32 v7, -v7, v13, v12
	v_div_fmas_f32 v7, v7, v9, v13
	v_div_fixup_f32 v6, v7, v6, v8
	v_bfe_u32 v7, v6, 16, 1
	s_movk_i32 s3, 0x7fff
	s_add_u32 s2, s4, s2
	v_add3_u32 v8, v6, v7, s3
	s_addc_u32 s3, s5, 0
	v_lshl_add_u64 v[6:7], s[2:3], 0, v[10:11]
	v_readlane_b32 s2, v252, 1
	v_add_co_u32_e32 v6, vcc, 0x42af8000, v6
	s_add_i32 s22, s22, s2
	s_sub_i32 s15, s15, s2
	v_addc_co_u32_e32 v7, vcc, 0, v7, vcc
	s_cmpk_gt_i32 s22, 0x1ff
	v_readlane_b32 s3, v252, 2
	global_store_short_d16_hi v[6:7], v8, off
	s_cbranch_scc0 .LBB0_1477

.LBB0_1744:
	s_and_saveexec_b64 s[50:51], s[38:39]
	s_lshl_b32 s52, s5, 10
	v_add_u32_e32 v188, s52, v180
	s_add_i32 s52, s52, 0x221fc
	v_mov_b32_e32 v189, s52
	ds_read_b32 v190, v188
	ds_read_b32 v191, v189
	s_waitcnt lgkmcnt(0)
	v_sub_f32_e32 v190, v191, v190
	v_exp_f32_e32 v190, v190
	v_add_u32_e32 v188, 0x4800, v180
	s_nop 0
	ds_write_b32 v188, v190
	s_or_b64 exec, exec, s[50:51]
	s_mul_i32 s2, s5, 0x11000
	s_add_i32 s2, s2, 0
	s_add_i32 s3, s23, s2
	v_add3_u32 v10, s3, v128, v88
	v_add_u32_e32 v44, 0x4000, v10
	v_cvt_pk_bf16_f32 v2, v28, v29
	v_cvt_pk_bf16_f32 v3, v30, v31
	v_cvt_pk_bf16_f32 v4, v32, v33
	v_cvt_pk_bf16_f32 v5, v34, v35
	ds_read2_b64 v[6:9], v44 offset0:128 offset1:132
	v_cvt_pk_bf16_f32 v48, v36, v37
	v_cvt_pk_bf16_f32 v49, v38, v39
	v_cvt_pk_bf16_f32 v50, v40, v41
	v_cvt_pk_bf16_f32 v51, v42, v43
	ds_read2_b64 v[44:47], v44 offset0:136 offset1:140
	s_waitcnt lgkmcnt(0)
	v_mfma_f32_16x16x32_bf16 v[6:9], v[2:5], v[6:9], 0
	s_lshl_b32 s5, s5, 10
	s_add_i32 s65, s5, 0
	s_add_i32 s65, s65, 0x22000
	v_mfma_f32_16x16x32_bf16 v[52:55], v[48:51], v[44:47], v[6:9]
	v_add_u32_e32 v44, 0x5000, v10
	v_add_u32_e32 v114, s2, v88
	v_lshl_add_u32 v182, v115, 2, s65
	s_nop 0
	ds_read2_b64 v[6:9], v44 offset0:160 offset1:164
	ds_read2_b64 v[44:47], v44 offset0:168 offset1:172
	s_waitcnt lgkmcnt(0)
	v_mfma_f32_16x16x32_bf16 v[6:9], v[2:5], v[6:9], 0
	s_mov_b64 s[42:43], -1
	s_andn2_b64 vcc, exec, s[10:11]
	v_mfma_f32_16x16x32_bf16 v[56:59], v[48:51], v[44:47], v[6:9]
	v_add_u32_e32 v44, 0x6000, v10
	v_add_u32_e32 v10, 0x7000, v10
	ds_read2_b64 v[60:63], v10 offset0:224 offset1:228
	s_nop 1
	ds_read2_b64 v[6:9], v44 offset0:192 offset1:196
	ds_read2_b64 v[44:47], v44 offset0:200 offset1:204
	s_waitcnt lgkmcnt(0)
	v_mfma_f32_16x16x32_bf16 v[6:9], v[2:5], v[6:9], 0
	v_mfma_f32_16x16x32_bf16 v[44:47], v[48:51], v[44:47], v[6:9]
	s_nop 6
	ds_read2_b64 v[6:9], v10 offset0:232 offset1:236
	v_mfma_f32_16x16x32_bf16 v[2:5], v[2:5], v[60:63], 0
	v_mov_b32_e32 v10, s65
	ds_read_b32 v181, v10 offset:508
	s_waitcnt lgkmcnt(0)
	v_mfma_f32_16x16x32_bf16 v[48:51], v[48:51], v[6:9], v[2:5]
	v_add_u32_e32 v6, s35, v127
	s_nop 2
	v_cndmask_b32_e64 v5, v59, v55, s[40:41]
	v_cndmask_b32_e64 v4, v58, v54, s[40:41]
	v_cndmask_b32_e64 v3, v57, v53, s[40:41]
	v_cndmask_b32_e64 v2, v56, v52, s[40:41]
	ds_write_b128 v6, v[2:5]
	v_cndmask_b32_e64 v5, v47, v51, s[40:41]
	v_cndmask_b32_e64 v4, v46, v50, s[40:41]
	v_cndmask_b32_e64 v3, v45, v49, s[40:41]
	v_cndmask_b32_e64 v2, v44, v48, s[40:41]
	ds_write_b128 v176, v[2:5] offset:1024
	v_mov_b32_e32 v2, v177
	s_waitcnt lgkmcnt(0)
	s_barrier
	s_nop 0
	v_and_b32_e32 v10, 15, v2
	v_or_b32_e32 v86, s18, v10
	v_lshl_add_u32 v3, v86, 2, s65
	v_mad_u64_u32 v[6:7], s[2:3], v2, s71, v[114:115]
	ds_read2st64_b32 v[76:77], v3 offset1:2
	ds_read2_b64 v[2:5], v6 offset1:4
	ds_read2_b64 v[64:67], v6 offset0:8 offset1:12
	ds_read_b128 v[60:63], v178
	ds_read_b128 v[72:75], v182
	ds_read_b128 v[68:71], v182 offset:64
	s_waitcnt lgkmcnt(0)
	v_lshlrev_b32_e32 v84, 16, v2
	v_and_b32_e32 v85, 0xffff0000, v2
	v_lshlrev_b32_e32 v82, 16, v3
	v_and_b32_e32 v83, 0xffff0000, v3
	v_lshlrev_b32_e32 v80, 16, v4
	v_and_b32_e32 v81, 0xffff0000, v4
	v_lshlrev_b32_e32 v78, 16, v5
	v_and_b32_e32 v79, 0xffff0000, v5
	s_cbranch_vccnz .LBB0_1746
	v_sub_f32_e32 v2, v76, v72
	v_sub_f32_e32 v3, v76, v73
	v_sub_f32_e32 v4, v76, v74
	v_sub_f32_e32 v5, v76, v75
	v_sub_f32_e32 v6, v76, v68
	v_sub_f32_e32 v7, v76, v69
	v_sub_f32_e32 v8, v76, v70
	v_sub_f32_e32 v9, v76, v71
	v_exp_f32_e32 v2, v2
	v_exp_f32_e32 v3, v3
	v_exp_f32_e32 v4, v4
	v_exp_f32_e32 v5, v5
	v_exp_f32_e32 v6, v6
	v_exp_f32_e32 v8, v8
	v_exp_f32_e32 v9, v9
	v_exp_f32_e32 v7, v7
	v_pk_mul_f32 v[2:3], v[2:3], v[84:85]
	v_pk_mul_f32 v[4:5], v[4:5], v[82:83]
	v_pk_mul_f32 v[8:9], v[8:9], v[78:79]
	v_pk_mul_f32 v[6:7], v[6:7], v[80:81]
	s_mov_b64 s[42:43], 0

.LBB0_1886:
	v_cndmask_b32_e64 v8, v48, v44, s[40:41]
	v_exp_f32_e32 v44, v116
	v_cndmask_b32_e64 v7, v51, v47, s[40:41]
	v_cndmask_b32_e64 v6, v50, v46, s[40:41]
	v_cndmask_b32_e64 v9, v49, v45, s[40:41]
	v_pk_add_f32 v[8:9], v[8:9], v[76:77]
	v_pk_add_f32 v[6:7], v[6:7], v[78:79]
	s_nop 0
	v_pk_fma_f32 v[2:3], v[44:45], v[8:9], v[2:3] op_sel_hi:[0,1,1]
	v_pk_fma_f32 v[4:5], v[44:45], v[6:7], v[4:5] op_sel_hi:[0,1,1]
	v_lshl_add_u32 v10, v10, 12, s1
	v_cvt_pk_bf16_f32 v2, v2, v3
	v_cvt_pk_bf16_f32 v3, v4, v5
	v_lshl_add_u64 v[4:5], v[10:11], 1, v[92:93]
	global_store_dwordx2 v[4:5], v[2:3], off
	v_mov_b32_e32 v2, s65
	ds_read_b32 v10, v2 offset:508
	s_sub_i32 s52, 0x26800, s65
	v_add_u32_e32 v192, s52, v182
	ds_read_b128 v[228:231], v192
	ds_read_b128 v[232:235], v192 offset:64
	ds_read_b128 v[236:239], v192 offset:128
	ds_read_b128 v[240:243], v192 offset:192
	ds_read_b128 v[244:247], v192 offset:256
	ds_read_b128 v[212:215], v192 offset:320
	ds_read_b128 v[216:219], v192 offset:384
	ds_read_b128 v[196:199], v192 offset:448
	v_lshlrev_b32_e32 v4, 16, v24
	v_and_b32_e32 v5, 0xffff0000, v24
	v_lshlrev_b32_e32 v6, 16, v25
	v_and_b32_e32 v7, 0xffff0000, v25
	s_waitcnt lgkmcnt(0)
	v_lshlrev_b32_e32 v8, 16, v27
	v_and_b32_e32 v9, 0xffff0000, v27
	v_lshlrev_b32_e32 v44, 16, v12
	v_pk_mul_f32 v[2:3], v[228:229], v[4:5]
	v_and_b32_e32 v45, 0xffff0000, v12
	v_cvt_pk_bf16_f32 v2, v2, v3
	s_nor_b64 s[2:3], s[36:37], s[30:31]
	v_pk_mul_f32 v[4:5], v[230:231], v[6:7]
	s_nop 0
	v_cvt_pk_bf16_f32 v3, v4, v5
	v_lshlrev_b32_e32 v6, 16, v26
	v_and_b32_e32 v7, 0xffff0000, v26
	v_pk_mul_f32 v[4:5], v[232:233], v[6:7]
	s_nop 0
	v_cvt_pk_bf16_f32 v4, v4, v5
	s_nop 0
	v_pk_mul_f32 v[6:7], v[234:235], v[8:9]
	s_nop 0
	v_cvt_pk_bf16_f32 v5, v6, v7
	v_lshlrev_b32_e32 v8, 16, v20
	v_and_b32_e32 v9, 0xffff0000, v20
	v_lshlrev_b32_e32 v20, 16, v21
	v_pk_mul_f32 v[6:7], v[236:237], v[8:9]
	v_and_b32_e32 v21, 0xffff0000, v21
	v_cvt_pk_bf16_f32 v6, v6, v7
	s_nop 0
	v_pk_mul_f32 v[8:9], v[238:239], v[20:21]
	s_nop 0
	v_cvt_pk_bf16_f32 v7, v8, v9
	v_lshlrev_b32_e32 v20, 16, v22
	v_and_b32_e32 v21, 0xffff0000, v22
	v_lshlrev_b32_e32 v22, 16, v23
	v_pk_mul_f32 v[8:9], v[240:241], v[20:21]
	v_and_b32_e32 v23, 0xffff0000, v23
	v_cvt_pk_bf16_f32 v8, v8, v9
	s_nop 0
	v_pk_mul_f32 v[20:21], v[242:243], v[22:23]
	s_nop 0
	v_cvt_pk_bf16_f32 v9, v20, v21
	v_lshlrev_b32_e32 v22, 16, v16
	v_and_b32_e32 v23, 0xffff0000, v16
	v_pk_mul_f32 v[20:21], v[244:245], v[22:23]
	s_nop 0
	v_cvt_pk_bf16_f32 v16, v20, v21
	v_lshlrev_b32_e32 v22, 16, v17
	v_and_b32_e32 v23, 0xffff0000, v17
	v_pk_mul_f32 v[20:21], v[246:247], v[22:23]
	s_nop 0
	v_cvt_pk_bf16_f32 v17, v20, v21
	v_lshlrev_b32_e32 v22, 16, v18
	v_and_b32_e32 v23, 0xffff0000, v18
	v_add_u32_e32 v52, v114, v174
	v_pk_mul_f32 v[20:21], v[212:213], v[22:23]
	v_lshlrev_b32_e32 v22, 16, v19
	v_cvt_pk_bf16_f32 v18, v20, v21
	v_and_b32_e32 v23, 0xffff0000, v19
	v_add_u32_e32 v48, 0x8800, v52
	v_pk_mul_f32 v[20:21], v[214:215], v[22:23]
	s_nop 0
	v_cvt_pk_bf16_f32 v19, v20, v21
	s_waitcnt lgkmcnt(0)
	s_nop 0
	v_pk_mul_f32 v[20:21], v[216:217], v[44:45]
	s_nop 0
	v_cvt_pk_bf16_f32 v12, v20, v21
	v_lshlrev_b32_e32 v22, 16, v13
	v_and_b32_e32 v23, 0xffff0000, v13
	v_pk_mul_f32 v[20:21], v[218:219], v[22:23]
	s_nop 0
	v_cvt_pk_bf16_f32 v13, v20, v21
	v_lshlrev_b32_e32 v22, 16, v14
	v_and_b32_e32 v23, 0xffff0000, v14
	v_pk_mul_f32 v[20:21], v[196:197], v[22:23]
	s_nop 0
	v_cvt_pk_bf16_f32 v14, v20, v21
	v_exp_f32_e32 v10, v181
	v_lshlrev_b32_e32 v22, 16, v15
	v_and_b32_e32 v23, 0xffff0000, v15
	v_pk_mul_f32 v[20:21], v[198:199], v[22:23]
	v_pk_mul_f32 v[30:31], v[30:31], v[10:11] op_sel_hi:[1,0]
	v_cvt_pk_bf16_f32 v15, v20, v21
	ds_read2_b64 v[20:23], v48 offset1:4
	ds_read2_b64 v[24:27], v48 offset0:8 offset1:12
	ds_read2_b64 v[44:47], v48 offset0:16 offset1:20
	ds_read2_b64 v[48:51], v48 offset0:24 offset1:28
	v_pk_mul_f32 v[28:29], v[28:29], v[10:11] op_sel_hi:[1,0]
	v_pk_mul_f32 v[34:35], v[34:35], v[10:11] op_sel_hi:[1,0]
	v_pk_mul_f32 v[32:33], v[32:33], v[10:11] op_sel_hi:[1,0]
	s_waitcnt lgkmcnt(0)
	v_mfma_f32_16x16x32_bf16 v[20:23], v[20:23], v[2:5], v[28:31]
	v_mul_f32_e64 v38, v38, v10
	v_mul_f32_e64 v39, v39, v10
	v_pk_mul_f32 v[36:37], v[36:37], v[10:11] op_sel_hi:[1,0]
	v_pk_mul_f32 v[42:43], v[42:43], v[10:11] op_sel_hi:[1,0]
	v_mfma_f32_16x16x32_bf16 v[20:23], v[24:27], v[6:9], v[20:23]
	v_mul_f32_e64 v40, v40, v10
	v_mul_f32_e64 v41, v41, v10
	v_mfma_f32_16x16x32_bf16 v[20:23], v[44:47], v[16:19], v[20:23]
	v_mfma_f32_16x16x32_bf16 v[28:31], v[48:51], v[12:15], v[20:23]
	v_add_u32_e32 v48, 0x9800, v52
	s_nop 5
	ds_read2_b64 v[20:23], v48 offset0:32 offset1:36
	ds_read2_b64 v[24:27], v48 offset0:40 offset1:44
	ds_read2_b64 v[44:47], v48 offset0:48 offset1:52
	ds_read2_b64 v[48:51], v48 offset0:56 offset1:60
	s_waitcnt lgkmcnt(0)
	v_mfma_f32_16x16x32_bf16 v[20:23], v[20:23], v[2:5], v[32:35]
	v_mfma_f32_16x16x32_bf16 v[20:23], v[24:27], v[6:9], v[20:23]
	v_mfma_f32_16x16x32_bf16 v[20:23], v[44:47], v[16:19], v[20:23]
	v_mfma_f32_16x16x32_bf16 v[32:35], v[48:51], v[12:15], v[20:23]
	v_add_u32_e32 v48, 0xa800, v52
	s_nop 5
	ds_read2_b64 v[20:23], v48 offset0:64 offset1:68
	ds_read2_b64 v[24:27], v48 offset0:72 offset1:76
	ds_read2_b64 v[44:47], v48 offset0:80 offset1:84
	ds_read2_b64 v[48:51], v48 offset0:88 offset1:92
	s_waitcnt lgkmcnt(0)
	v_mfma_f32_16x16x32_bf16 v[20:23], v[20:23], v[2:5], v[36:39]
	v_mfma_f32_16x16x32_bf16 v[20:23], v[24:27], v[6:9], v[20:23]
	v_mfma_f32_16x16x32_bf16 v[20:23], v[44:47], v[16:19], v[20:23]
	v_mfma_f32_16x16x32_bf16 v[36:39], v[48:51], v[12:15], v[20:23]
	s_nop 6
	v_add_u32_e32 v20, v114, v175
	v_add_u32_e32 v48, 0x8800, v20
	ds_read2_b64 v[20:23], v48 offset1:4
	ds_read2_b64 v[24:27], v48 offset0:8 offset1:12
	ds_read2_b64 v[44:47], v48 offset0:16 offset1:20
	ds_read2_b64 v[48:51], v48 offset0:24 offset1:28
	s_waitcnt lgkmcnt(0)
	v_mfma_f32_16x16x32_bf16 v[2:5], v[20:23], v[2:5], v[40:43]
	v_mfma_f32_16x16x32_bf16 v[2:5], v[24:27], v[6:9], v[2:5]
	v_mfma_f32_16x16x32_bf16 v[2:5], v[44:47], v[16:19], v[2:5]
	v_mfma_f32_16x16x32_bf16 v[40:43], v[48:51], v[12:15], v[2:5]
	s_and_saveexec_b64 s[30:31], s[2:3]
	s_cbranch_execz .LBB0_1649
	s_xor_b32 s2, s5, 0x400
	s_waitcnt vmcnt(0)
	s_nop 2
	v_mul_f32_e32 v2, 0x3fb8aa3b, v89
	v_add_u32_e32 v3, s2, v180
	ds_write2st64_b32 v3, v2, v95 offset1:2
	s_branch .LBB0_1649
